# MLA attention unit: tile-0 K/k_pe/V loads also issued at unit start
# baseline (speedup 1.0000x reference)
; template <int DQK, bool MOBA>
; __device__ __forceinline__ void attn_unit(const Args& A, int b, int h, int qb, lptr lds) {
;     ...
;     int tid_o = threadIdx.x; asm volatile("" : "+v"(tid_o));
;     const int tid = tid_o, lane = tid & 63, r32 = lane & 31, hi = lane >> 5;
;     const int wid = __builtin_amdgcn_readfirstlane(tid >> 6);
;     const int tb = b * SEQ, q0 = qb * 256, own = qb, bh = b * NH + h;
;     const int qrow = tb + q0 + wid * 32 + r32;
;     const int qrel = wid * 32 + r32;
;     __syncthreads();
;     bf16x8 qf[NS];
;     {
;         const bf16* qp = A.Q + (size_t)qrow * A.q_pitch + h * DQK + 8 * hi;
; #pragma unroll
;         for (int s = 0; s < NS; ++s) qf[s] = *(const bf16x8*)(qp + 16 * s);
.LBB0_809:
	s_lshl_b32 s0, s21, 2
	s_add_i32 s0, s0, s19
	s_ashr_i32 s1, s0, 31
	s_lshr_b32 s1, s1, 29
	s_add_i32 s1, s0, s1
	v_mov_b32_e32 v106, v202
	s_and_b32 s4, s1, -8
	s_lshl_b32 s1, s1, 8
	v_readfirstlane_b32 s5, v106
	s_and_b32 s24, s1, 0xfffff800
	s_lshl_b32 s13, s22, 8
	s_ashr_i32 s15, s5, 1
	s_sub_i32 s0, s0, s4
	s_add_i32 s4, s13, s24
	s_and_b32 s23, s15, 0xffffffe0
	v_and_b32_e32 v108, 31, v106
	s_add_i32 s1, s23, s4
	v_or_b32_e32 v184, s1, v108
	v_mov_b32_e32 v214, 0x20000
	ds_read_b32 v216, v214 offset:80
	v_mov_b32_e32 v217, 0
	s_waitcnt lgkmcnt(0)
	v_lshl_add_u64 v[0:1], s[88:89], 0, v[216:217]
	v_mad_i64_i32 v[0:1], s[6:7], v184, s11, v[0:1]
	s_mul_i32 s6, s0, 0xc0
	v_bfe_u32 v107, v106, 5, 1
	s_ashr_i32 s7, s6, 31
	v_lshl_add_u64 v[0:1], s[6:7], 1, v[0:1]
	v_lshlrev_b32_e32 v180, 4, v107
	v_lshl_add_u64 v[82:83], v[0:1], 0, v[180:181]
	v_and_b32_e32 v76, 32, v106
	s_barrier
	v_lshrrev_b32_e32 v234, 4, v106
	v_add_u32_e32 v234, s4, v234
	v_and_b32_e32 v235, 15, v106
	v_lshlrev_b32_e32 v235, 4, v235
	v_lshl_add_u32 v235, s0, 8, v235
	v_lshl_add_u32 v236, v234, 11, v235
	v_mov_b32_e32 v237, 0
	v_add_u32_e32 v240, 0x10000, v236
	v_mov_b32_e32 v241, 0
	v_lshrrev_b32_e32 v242, 3, v106
	v_add_u32_e32 v242, s4, v242
	v_and_b32_e32 v243, 7, v106
	v_lshlrev_b32_e32 v243, 4, v243
	v_lshl_add_u32 v242, v242, 7, v243
	v_mov_b32_e32 v243, 0
	v_lshl_add_u64 v[238:239], s[90:91], 0, v[236:237]
	v_lshl_add_u64 v[244:245], s[90:91], 0, v[240:241]
	global_load_dwordx4 v[214:217], v[238:239], off
	global_load_dwordx4 v[218:221], v[244:245], off
	v_lshl_add_u64 v[238:239], s[86:87], 0, v[242:243]
	global_load_dwordx4 v[222:225], v[238:239], off
	v_lshl_add_u64 v[244:245], s[92:93], 0, v[240:241]
	v_lshl_add_u64 v[238:239], s[92:93], 0, v[236:237]
	global_load_dwordx4 v[226:229], v[244:245], off
	global_load_dwordx4 v[230:233], v[238:239], off
	global_load_dwordx4 v[84:87], v[82:83], off offset:224
	global_load_dwordx4 v[90:93], v[82:83], off offset:192
	global_load_dwordx4 v[98:101], v[82:83], off offset:160
	global_load_dwordx4 v[68:71], v[82:83], off offset:128
	global_load_dwordx4 v[60:63], v[82:83], off offset:96
	global_load_dwordx4 v[56:59], v[82:83], off offset:64
	global_load_dwordx4 v[48:51], v76, s[28:29] offset:16
	global_load_dwordx4 v[52:55], v76, s[28:29]
	global_load_dwordx4 v[40:43], v76, s[28:29] offset:80
	global_load_dwordx4 v[44:47], v76, s[28:29] offset:64
	global_load_dwordx4 v[32:35], v76, s[28:29] offset:144
	global_load_dwordx4 v[36:39], v76, s[28:29] offset:128
	global_load_dwordx4 v[24:27], v76, s[28:29] offset:208
	global_load_dwordx4 v[28:31], v76, s[28:29] offset:192
	global_load_dwordx4 v[64:67], v[82:83], off
	global_load_dwordx4 v[112:115], v[82:83], off offset:32
	global_load_dwordx4 v[16:19], v76, s[28:29] offset:272
	global_load_dwordx4 v[20:23], v76, s[28:29] offset:256
	global_load_dwordx4 v[8:11], v76, s[28:29] offset:336
	global_load_dwordx4 v[12:15], v76, s[28:29] offset:320
	v_and_b32_e32 v1, 64, v206
	v_xor_b32_e32 v0, 32, v206
	v_add_u32_e32 v109, 64, v1
	v_cmp_lt_i32_e32 vcc, v0, v109
	v_ashrrev_i32_e32 v185, 31, v184
	v_mov_b32_e32 v77, v181
	v_cndmask_b32_e32 v0, v206, v0, vcc
	v_lshlrev_b32_e32 v196, 2, v0
	global_load_dwordx4 v[0:3], v[82:83], off offset:256
	global_load_dwordx4 v[4:7], v[82:83], off offset:288
	v_and_b32_e32 v110, 63, v106
	s_lshl_b32 s25, s22, 2
	s_ashr_i32 s5, s4, 31
	s_add_i32 s26, s25, 4
	s_lshl_b64 s[44:45], s[4:5], 11
	s_add_u32 s1, s90, s44
	s_addc_u32 s5, s91, s45
	s_lshl_b32 s42, s0, 7
	s_ashr_i32 s43, s42, 31
	s_lshl_b64 s[6:7], s[42:43], 1
	s_add_u32 s0, s1, s6
	s_addc_u32 s1, s5, s7
	s_mov_b32 s5, 2
	s_mov_b32 s27, 0
	s_waitcnt vmcnt(21)
	v_and_b32_e32 v73, 0xffff0000, v87
	s_waitcnt vmcnt(7)
	v_and_b32_e32 v201, 0xffff0000, v64
	v_lshlrev_b32_e32 v200, 16, v64
	v_and_b32_e32 v195, 0xffff0000, v65
	v_lshlrev_b32_e32 v194, 16, v65
	v_pk_mul_f32 v[64:65], v[200:201], v[200:201]
	v_pk_mul_f32 v[198:199], v[194:195], v[194:195]
	v_add_f32_e32 v64, v64, v65
	v_and_b32_e32 v193, 0xffff0000, v66
	v_lshlrev_b32_e32 v192, 16, v66
	v_add_f32_e32 v64, v198, v64
	v_and_b32_e32 v189, 0xffff0000, v67
	v_lshlrev_b32_e32 v188, 16, v67
	v_pk_mul_f32 v[66:67], v[192:193], v[192:193]
	v_add_f32_e32 v64, v199, v64
	v_add_f32_e32 v64, v66, v64
	v_pk_mul_f32 v[190:191], v[188:189], v[188:189]
	v_add_f32_e32 v64, v67, v64
	s_waitcnt vmcnt(6)
; __device__ __forceinline__ float bf2f(unsigned short v) { return __uint_as_float(((unsigned)v) << 16); }
; template <int DQK, bool MOBA>
; __device__ __forceinline__ void attn_unit(const Args& A, int b, int h, int qb, lptr lds) {
;     ...
;     {
;         float ssn = 0.f;
; #pragma unroll
;         for (int s = 0; s < 8; ++s)
; #pragma unroll
;             for (int e = 0; e < 8; ++e) { const float f = bf2f((unsigned short)qf[s][e]); ssn += f * f; }
;         ssn += __shfl_xor(ssn, 32);
	v_and_b32_e32 v187, 0xffff0000, v112
	v_lshlrev_b32_e32 v186, 16, v112
	v_add_f32_e32 v64, v190, v64
	v_and_b32_e32 v177, 0xffff0000, v113
	v_lshlrev_b32_e32 v176, 16, v113
	v_pk_mul_f32 v[112:113], v[186:187], v[186:187]
	v_add_f32_e32 v64, v191, v64
	v_add_f32_e32 v64, v112, v64
	v_pk_mul_f32 v[178:179], v[176:177], v[176:177]
	v_add_f32_e32 v64, v113, v64
	v_and_b32_e32 v175, 0xffff0000, v114
	v_lshlrev_b32_e32 v174, 16, v114
	v_add_f32_e32 v64, v178, v64
	v_and_b32_e32 v171, 0xffff0000, v115
	v_lshlrev_b32_e32 v170, 16, v115
	v_pk_mul_f32 v[114:115], v[174:175], v[174:175]
	v_add_f32_e32 v64, v179, v64
	v_add_f32_e32 v64, v114, v64
	v_pk_mul_f32 v[172:173], v[170:171], v[170:171]
	v_add_f32_e32 v64, v115, v64
	v_and_b32_e32 v169, 0xffff0000, v56
	v_lshlrev_b32_e32 v168, 16, v56
	v_add_f32_e32 v64, v172, v64
	v_and_b32_e32 v165, 0xffff0000, v57
	v_lshlrev_b32_e32 v164, 16, v57
	v_pk_mul_f32 v[56:57], v[168:169], v[168:169]
	v_add_f32_e32 v64, v173, v64
	v_add_f32_e32 v56, v56, v64
	v_pk_mul_f32 v[166:167], v[164:165], v[164:165]
	v_add_f32_e32 v56, v57, v56
	v_and_b32_e32 v163, 0xffff0000, v58
	v_lshlrev_b32_e32 v162, 16, v58
	v_add_f32_e32 v56, v166, v56
	v_and_b32_e32 v159, 0xffff0000, v59
	v_lshlrev_b32_e32 v158, 16, v59
	v_pk_mul_f32 v[58:59], v[162:163], v[162:163]
	v_add_f32_e32 v56, v167, v56
	v_add_f32_e32 v56, v58, v56
	v_pk_mul_f32 v[160:161], v[158:159], v[158:159]
	v_add_f32_e32 v56, v59, v56
	v_and_b32_e32 v157, 0xffff0000, v60
	v_lshlrev_b32_e32 v156, 16, v60
	v_add_f32_e32 v56, v160, v56
	v_and_b32_e32 v155, 0xffff0000, v61
	v_lshlrev_b32_e32 v154, 16, v61
	v_pk_mul_f32 v[60:61], v[156:157], v[156:157]
	v_add_f32_e32 v56, v161, v56
	v_add_f32_e32 v56, v60, v56
	v_pk_mul_f32 v[148:149], v[154:155], v[154:155]
	v_add_f32_e32 v56, v61, v56
	v_and_b32_e32 v153, 0xffff0000, v62
	v_lshlrev_b32_e32 v152, 16, v62
	v_add_f32_e32 v56, v148, v56
	v_and_b32_e32 v151, 0xffff0000, v63
	v_lshlrev_b32_e32 v150, 16, v63
	v_pk_mul_f32 v[62:63], v[152:153], v[152:153]
	v_add_f32_e32 v56, v149, v56
	v_add_f32_e32 v56, v62, v56
	v_pk_mul_f32 v[146:147], v[150:151], v[150:151]
	v_add_f32_e32 v56, v63, v56
	v_and_b32_e32 v105, 0xffff0000, v68
	v_lshlrev_b32_e32 v104, 16, v68
	v_add_f32_e32 v56, v146, v56
	v_and_b32_e32 v103, 0xffff0000, v69
	v_lshlrev_b32_e32 v102, 16, v69
	v_pk_mul_f32 v[68:69], v[104:105], v[104:105]
	v_add_f32_e32 v56, v147, v56
	v_add_f32_e32 v56, v68, v56
	v_pk_mul_f32 v[144:145], v[102:103], v[102:103]
	v_add_f32_e32 v56, v69, v56
	v_lshlrev_b32_e32 v72, 16, v87
	v_and_b32_e32 v75, 0xffff0000, v86
	v_lshlrev_b32_e32 v74, 16, v86
	v_and_b32_e32 v79, 0xffff0000, v85
	v_lshlrev_b32_e32 v78, 16, v85
	v_and_b32_e32 v81, 0xffff0000, v84
	v_lshlrev_b32_e32 v80, 16, v84
	v_and_b32_e32 v85, 0xffff0000, v93
	v_lshlrev_b32_e32 v84, 16, v93
	v_and_b32_e32 v87, 0xffff0000, v92
	v_lshlrev_b32_e32 v86, 16, v92
	v_and_b32_e32 v93, 0xffff0000, v101
	v_lshlrev_b32_e32 v92, 16, v101
	v_and_b32_e32 v95, 0xffff0000, v100
	v_lshlrev_b32_e32 v94, 16, v100
	v_and_b32_e32 v101, 0xffff0000, v71
	v_lshlrev_b32_e32 v100, 16, v71
	v_and_b32_e32 v71, 0xffff0000, v70
	v_lshlrev_b32_e32 v70, 16, v70
	v_add_f32_e32 v56, v144, v56
	v_pk_mul_f32 v[142:143], v[70:71], v[70:71]
	v_add_f32_e32 v56, v145, v56
	v_add_f32_e32 v56, v142, v56
	v_pk_mul_f32 v[140:141], v[100:101], v[100:101]
	v_add_f32_e32 v56, v143, v56
	v_and_b32_e32 v97, 0xffff0000, v99
	v_lshlrev_b32_e32 v96, 16, v99
	v_and_b32_e32 v99, 0xffff0000, v98
	v_lshlrev_b32_e32 v98, 16, v98
	v_add_f32_e32 v56, v140, v56
	v_pk_mul_f32 v[138:139], v[98:99], v[98:99]
	v_add_f32_e32 v56, v141, v56
	v_add_f32_e32 v56, v138, v56
	v_pk_mul_f32 v[136:137], v[96:97], v[96:97]
	v_add_f32_e32 v56, v139, v56
	v_add_f32_e32 v56, v136, v56
	v_pk_mul_f32 v[134:135], v[94:95], v[94:95]
	v_add_f32_e32 v56, v137, v56
	v_add_f32_e32 v56, v134, v56
	v_pk_mul_f32 v[132:133], v[92:93], v[92:93]
	v_add_f32_e32 v56, v135, v56
	v_and_b32_e32 v89, 0xffff0000, v91
	v_lshlrev_b32_e32 v88, 16, v91
	v_and_b32_e32 v91, 0xffff0000, v90
	v_lshlrev_b32_e32 v90, 16, v90
	v_add_f32_e32 v56, v132, v56
	v_pk_mul_f32 v[130:131], v[90:91], v[90:91]
	v_add_f32_e32 v56, v133, v56
	v_add_f32_e32 v56, v130, v56
	v_pk_mul_f32 v[128:129], v[88:89], v[88:89]
	v_add_f32_e32 v56, v131, v56
	v_add_f32_e32 v56, v128, v56
	v_pk_mul_f32 v[126:127], v[86:87], v[86:87]
	v_add_f32_e32 v56, v129, v56
	v_add_f32_e32 v56, v126, v56
	v_pk_mul_f32 v[124:125], v[84:85], v[84:85]
	v_add_f32_e32 v56, v127, v56
	v_add_f32_e32 v56, v124, v56
	v_pk_mul_f32 v[122:123], v[80:81], v[80:81]
	v_add_f32_e32 v56, v125, v56
	v_add_f32_e32 v56, v122, v56
	v_pk_mul_f32 v[120:121], v[78:79], v[78:79]
	v_add_f32_e32 v56, v123, v56
	v_add_f32_e32 v56, v120, v56
	v_pk_mul_f32 v[118:119], v[74:75], v[74:75]
	v_add_f32_e32 v56, v121, v56
	v_add_f32_e32 v56, v118, v56
	v_pk_mul_f32 v[116:117], v[72:73], v[72:73]
	v_add_f32_e32 v56, v119, v56
	v_add_f32_e32 v56, v116, v56
	v_add_f32_e32 v56, v117, v56
	global_load_dwordx4 v[60:63], v[82:83], off offset:320
	global_load_dwordx4 v[64:67], v[82:83], off offset:352
	global_load_dwordx4 v[138:141], v76, s[28:29] offset:400
	global_load_dwordx4 v[142:145], v76, s[28:29] offset:384
	ds_bpermute_b32 v57, v196, v56
	v_ashrrev_i32_e32 v199, 3, v106
	s_waitcnt lgkmcnt(0)
; __device__ __forceinline__ unsigned cvt_pk_bf16(float lo, float hi) { f32x2 v = {lo, hi}; bf16x2_t b = __builtin_convertvector(v, bf16x2_t); return __builtin_bit_cast(unsigned, b); }
; __device__ __forceinline__ float bf2f(unsigned short v) { return __uint_as_float(((unsigned)v) << 16); }
; template <int DQK, bool MOBA>
; __device__ __forceinline__ void attn_unit(const Args& A, int b, int h, int qb, lptr lds) {
;     ...
;         const float scn = __builtin_amdgcn_rsqf(ssn * (1.0f / 128.0f) + 1e-6f) * A.qscale;
; #pragma unroll
;         for (int s = 0; s < 8; ++s) {
;             const f32x4 g0 = *(const f32x4*)(A.gq_n + 16 * s + 8 * hi), g1 = *(const f32x4*)(A.gq_n + 16 * s + 8 * hi + 4);
;             u32x4 w;
;             w.x = cvt_pk_bf16(bf2f((unsigned short)qf[s][0]) * scn * g0[0], bf2f((unsigned short)qf[s][1]) * scn * g0[1]);
;             w.y = cvt_pk_bf16(bf2f((unsigned short)qf[s][2]) * scn * g0[2], bf2f((unsigned short)qf[s][3]) * scn * g0[3]);
;             w.z = cvt_pk_bf16(bf2f((unsigned short)qf[s][4]) * scn * g1[0], bf2f((unsigned short)qf[s][5]) * scn * g1[1]);
;             w.w = cvt_pk_bf16(bf2f((unsigned short)qf[s][6]) * scn * g1[2], bf2f((unsigned short)qf[s][7]) * scn * g1[3]);
;             qf[s] = __builtin_bit_cast(bf16x8, w);
;         }
;         if (DQK == 192) {
;             float ssr = 0.f;
; #pragma unroll
;             for (int s = 8; s < NS; ++s)
; #pragma unroll
;                 for (int e = 0; e < 8; ++e) { const float f = bf2f((unsigned short)qf[s][e]); ssr += f * f; }
;             ssr += __shfl_xor(ssr, 32);
;             const float scr = __builtin_amdgcn_rsqf(ssr * (1.0f / 64.0f) + 1e-6f);
; #pragma unroll
;             for (int sp = 0; sp < 2; ++sp) {
;                 const int i0 = 16 * sp + 8 * hi;
;                 float o1[8], o2[8];
;                 const f32x4 ga0 = *(const f32x4*)(A.gq_r + i0), ga1 = *(const f32x4*)(A.gq_r + i0 + 4), gb0 = *(const f32x4*)(A.gq_r + 32 + i0), gb1 = *(const f32x4*)(A.gq_r + 32 + i0 + 4);
;                 const f32x4 cc0 = *(const f32x4*)(A.cosT + (size_t)qrow * 32 + i0), cc1 = *(const f32x4*)(A.cosT + (size_t)qrow * 32 + i0 + 4);
;                 const f32x4 ss0 = *(const f32x4*)(A.sinT + (size_t)qrow * 32 + i0), ss1 = *(const f32x4*)(A.sinT + (size_t)qrow * 32 + i0 + 4);
	v_add_f32_e32 v56, v56, v57
	v_fmamk_f32 v56, v56, 0x3c000000, v204
	v_rsq_f32_e32 v68, v56
	global_load_dwordx4 v[56:59], v76, s[28:29] offset:464
	global_load_dwordx4 v[146:149], v76, s[28:29] offset:448
	v_mul_f32_e32 v68, 0x3dd53b94, v68
	v_pk_mul_f32 v[82:83], v[68:69], v[200:201] op_sel_hi:[0,1]
	v_pk_mul_f32 v[52:53], v[52:53], v[82:83]
	s_nop 0
	v_cvt_pk_bf16_f32 v112, v52, v53
	v_pk_mul_f32 v[52:53], v[68:69], v[194:195] op_sel_hi:[0,1]
	v_pk_mul_f32 v[52:53], v[54:55], v[52:53]
	s_nop 0
	v_cvt_pk_bf16_f32 v113, v52, v53
	v_pk_mul_f32 v[52:53], v[68:69], v[192:193] op_sel_hi:[0,1]
	v_pk_mul_f32 v[48:49], v[48:49], v[52:53]
	s_nop 0
	v_cvt_pk_bf16_f32 v114, v48, v49
	v_pk_mul_f32 v[48:49], v[68:69], v[188:189] op_sel_hi:[0,1]
	v_pk_mul_f32 v[48:49], v[50:51], v[48:49]
	v_mov_b32_e32 v189, v181
	v_cvt_pk_bf16_f32 v115, v48, v49
	v_pk_mul_f32 v[48:49], v[68:69], v[186:187] op_sel_hi:[0,1]
	v_pk_mul_f32 v[44:45], v[44:45], v[48:49]
	v_mov_b32_e32 v187, v181
	v_cvt_pk_bf16_f32 v116, v44, v45
	v_pk_mul_f32 v[44:45], v[68:69], v[176:177] op_sel_hi:[0,1]
	v_pk_mul_f32 v[44:45], v[46:47], v[44:45]
	s_nop 0
	v_cvt_pk_bf16_f32 v117, v44, v45
	v_pk_mul_f32 v[44:45], v[68:69], v[174:175] op_sel_hi:[0,1]
	v_pk_mul_f32 v[40:41], v[40:41], v[44:45]
	s_nop 0
	v_cvt_pk_bf16_f32 v118, v40, v41
	v_pk_mul_f32 v[40:41], v[68:69], v[170:171] op_sel_hi:[0,1]
	v_pk_mul_f32 v[40:41], v[42:43], v[40:41]
	s_nop 0
	v_cvt_pk_bf16_f32 v119, v40, v41
	v_pk_mul_f32 v[40:41], v[68:69], v[168:169] op_sel_hi:[0,1]
	v_pk_mul_f32 v[36:37], v[36:37], v[40:41]
	s_waitcnt vmcnt(5)
	v_and_b32_e32 v169, 0xffff0000, v61
	v_cvt_pk_bf16_f32 v120, v36, v37
	v_pk_mul_f32 v[36:37], v[68:69], v[164:165] op_sel_hi:[0,1]
	v_pk_mul_f32 v[36:37], v[38:39], v[36:37]
	v_and_b32_e32 v165, 0xffff0000, v1
	v_cvt_pk_bf16_f32 v121, v36, v37
	v_pk_mul_f32 v[36:37], v[68:69], v[162:163] op_sel_hi:[0,1]
	v_pk_mul_f32 v[32:33], v[32:33], v[36:37]
	v_lshlrev_b32_e32 v164, 16, v1
	v_cvt_pk_bf16_f32 v122, v32, v33
	v_pk_mul_f32 v[32:33], v[68:69], v[158:159] op_sel_hi:[0,1]
	v_pk_mul_f32 v[32:33], v[34:35], v[32:33]
	v_and_b32_e32 v1, 0xffff0000, v0
	v_cvt_pk_bf16_f32 v123, v32, v33
	v_pk_mul_f32 v[32:33], v[68:69], v[156:157] op_sel_hi:[0,1]
	v_pk_mul_f32 v[28:29], v[28:29], v[32:33]
	v_lshlrev_b32_e32 v0, 16, v0
	v_cvt_pk_bf16_f32 v124, v28, v29
	v_pk_mul_f32 v[28:29], v[68:69], v[154:155] op_sel_hi:[0,1]
	v_pk_mul_f32 v[28:29], v[30:31], v[28:29]
	v_pk_mul_f32 v[172:173], v[0:1], v[0:1]
	v_cvt_pk_bf16_f32 v125, v28, v29
	v_pk_mul_f32 v[28:29], v[68:69], v[152:153] op_sel_hi:[0,1]
	v_pk_mul_f32 v[24:25], v[24:25], v[28:29]
	global_load_dwordx4 v[28:31], v76, s[30:31] offset:16
	global_load_dwordx4 v[32:35], v76, s[30:31]
	global_load_dwordx4 v[36:39], v76, s[30:31] offset:144
	global_load_dwordx4 v[40:43], v76, s[30:31] offset:128
	v_cvt_pk_bf16_f32 v126, v24, v25
	v_pk_mul_f32 v[24:25], v[68:69], v[150:151] op_sel_hi:[0,1]
	v_pk_mul_f32 v[24:25], v[26:27], v[24:25]
	v_pk_mul_f32 v[166:167], v[164:165], v[164:165]
	v_cvt_pk_bf16_f32 v127, v24, v25
	v_pk_mul_f32 v[24:25], v[68:69], v[104:105] op_sel_hi:[0,1]
	v_pk_mul_f32 v[20:21], v[20:21], v[24:25]
	v_and_b32_e32 v151, 0xffff0000, v3
	v_cvt_pk_bf16_f32 v128, v20, v21
	v_pk_mul_f32 v[20:21], v[68:69], v[102:103] op_sel_hi:[0,1]
	v_pk_mul_f32 v[20:21], v[22:23], v[20:21]
	v_lshlrev_b32_e32 v150, 16, v3
	v_cvt_pk_bf16_f32 v129, v20, v21
	v_pk_mul_f32 v[20:21], v[68:69], v[70:71] op_sel_hi:[0,1]
	v_pk_mul_f32 v[16:17], v[16:17], v[20:21]
	v_and_b32_e32 v3, 0xffff0000, v2
	v_cvt_pk_bf16_f32 v130, v16, v17
	v_pk_mul_f32 v[16:17], v[68:69], v[100:101] op_sel_hi:[0,1]
	v_pk_mul_f32 v[16:17], v[18:19], v[16:17]
	v_lshlrev_b32_e32 v2, 16, v2
	v_cvt_pk_bf16_f32 v131, v16, v17
	v_pk_mul_f32 v[16:17], v[68:69], v[98:99] op_sel_hi:[0,1]
	v_pk_mul_f32 v[12:13], v[12:13], v[16:17]
	v_pk_mul_f32 v[160:161], v[2:3], v[2:3]
	v_cvt_pk_bf16_f32 v132, v12, v13
	v_pk_mul_f32 v[12:13], v[68:69], v[96:97] op_sel_hi:[0,1]
	v_pk_mul_f32 v[12:13], v[14:15], v[12:13]
	v_pk_mul_f32 v[154:155], v[150:151], v[150:151]
	v_cvt_pk_bf16_f32 v133, v12, v13
	v_pk_mul_f32 v[12:13], v[68:69], v[94:95] op_sel_hi:[0,1]
	v_pk_mul_f32 v[8:9], v[8:9], v[12:13]
	v_and_b32_e32 v105, 0xffff0000, v5
	v_cvt_pk_bf16_f32 v134, v8, v9
	v_pk_mul_f32 v[8:9], v[68:69], v[92:93] op_sel_hi:[0,1]
	v_pk_mul_f32 v[8:9], v[10:11], v[8:9]
	v_lshlrev_b32_e32 v104, 16, v5
	v_cvt_pk_bf16_f32 v135, v8, v9
	v_pk_mul_f32 v[8:9], v[68:69], v[90:91] op_sel_hi:[0,1]
	s_waitcnt vmcnt(6)
	v_pk_mul_f32 v[8:9], v[142:143], v[8:9]
	v_and_b32_e32 v5, 0xffff0000, v4
	v_cvt_pk_bf16_f32 v136, v8, v9
	v_pk_mul_f32 v[8:9], v[68:69], v[88:89] op_sel_hi:[0,1]
	v_pk_mul_f32 v[8:9], v[144:145], v[8:9]
	v_lshlrev_b32_e32 v4, 16, v4
	v_cvt_pk_bf16_f32 v137, v8, v9
	v_pk_mul_f32 v[8:9], v[68:69], v[86:87] op_sel_hi:[0,1]
	v_pk_mul_f32 v[8:9], v[138:139], v[8:9]
	v_pk_mul_f32 v[142:143], v[104:105], v[104:105]
	v_cvt_pk_bf16_f32 v138, v8, v9
	v_pk_mul_f32 v[8:9], v[68:69], v[84:85] op_sel_hi:[0,1]
	v_pk_mul_f32 v[8:9], v[140:141], v[8:9]
	v_lshlrev_b32_e32 v168, 16, v61
	v_cvt_pk_bf16_f32 v139, v8, v9
	v_pk_mul_f32 v[8:9], v[68:69], v[80:81] op_sel_hi:[0,1]
	s_waitcnt vmcnt(4)
; __device__ __forceinline__ float bf2f(unsigned short v) { return __uint_as_float(((unsigned)v) << 16); }
; template <int DQK, bool MOBA>
; __device__ __forceinline__ void attn_unit(const Args& A, int b, int h, int qb, lptr lds) {
;     ...
;             for (int sp = 0; sp < 2; ++sp) {
;                 const int i0 = 16 * sp + 8 * hi;
;                 float o1[8], o2[8];
;                 const f32x4 ga0 = *(const f32x4*)(A.gq_r + i0), ga1 = *(const f32x4*)(A.gq_r + i0 + 4), gb0 = *(const f32x4*)(A.gq_r + 32 + i0), gb1 = *(const f32x4*)(A.gq_r + 32 + i0 + 4);
;                 const f32x4 cc0 = *(const f32x4*)(A.cosT + (size_t)qrow * 32 + i0), cc1 = *(const f32x4*)(A.cosT + (size_t)qrow * 32 + i0 + 4);
;                 const f32x4 ss0 = *(const f32x4*)(A.sinT + (size_t)qrow * 32 + i0), ss1 = *(const f32x4*)(A.sinT + (size_t)qrow * 32 + i0 + 4);
; #pragma unroll
;                 for (int e = 0; e < 8; ++e) {
;                     const float x1 = bf2f((unsigned short)qf[(NS == 12 ? 8 : 0) + sp][e]) * scr * (e < 4 ? ga0[e & 3] : ga1[e & 3]);
;                     const float x2 = bf2f((unsigned short)qf[(NS == 12 ? 10 : 0) + sp][e]) * scr * (e < 4 ? gb0[e & 3] : gb1[e & 3]);
;                     const float c = e < 4 ? cc0[e & 3] : cc1[e & 3], sn = e < 4 ? ss0[e & 3] : ss1[e & 3];
;                     o1[e] = (x1 * c - x2 * sn) * A.qscale; o2[e] = (x2 * c + x1 * sn) * A.qscale;
;                 }
	v_pk_mul_f32 v[8:9], v[146:147], v[8:9]
	v_pk_mul_f32 v[146:147], v[4:5], v[4:5]
	v_cvt_pk_bf16_f32 v140, v8, v9
	v_pk_mul_f32 v[8:9], v[68:69], v[78:79] op_sel_hi:[0,1]
	v_pk_mul_f32 v[70:71], v[148:149], v[8:9]
	v_lshlrev_b64 v[8:9], 7, v[184:185]
	v_lshl_add_u64 v[10:11], s[76:77], 0, v[8:9]
	v_lshl_add_u64 v[12:13], v[10:11], 0, v[76:77]
	global_load_dwordx4 v[44:47], v[12:13], off offset:16
	global_load_dwordx4 v[48:51], v[12:13], off
	v_lshl_add_u64 v[8:9], s[78:79], 0, v[8:9]
	v_lshl_add_u64 v[24:25], v[8:9], 0, v[76:77]
	global_load_dwordx4 v[52:55], v[24:25], off offset:16
	global_load_dwordx4 v[78:81], v[24:25], off
	global_load_dwordx4 v[20:23], v76, s[30:31] offset:80
	global_load_dwordx4 v[82:85], v76, s[30:31] offset:64
	global_load_dwordx4 v[16:19], v76, s[30:31] offset:208
	global_load_dwordx4 v[86:89], v76, s[30:31] offset:192
	global_load_dwordx4 v[8:11], v[12:13], off offset:80
	global_load_dwordx4 v[90:93], v[12:13], off offset:64
	s_nop 0
	global_load_dwordx4 v[12:15], v[24:25], off offset:80
	global_load_dwordx4 v[94:97], v[24:25], off offset:64
	v_add_f32_e32 v69, v172, v173
	v_add_f32_e32 v69, v166, v69
	v_add_f32_e32 v69, v167, v69
	v_add_f32_e32 v69, v160, v69
	v_add_f32_e32 v69, v161, v69
	v_add_f32_e32 v69, v154, v69
	v_add_f32_e32 v69, v155, v69
	v_add_f32_e32 v69, v146, v69
	v_add_f32_e32 v69, v147, v69
	v_and_b32_e32 v25, 0xffff0000, v7
	v_lshlrev_b32_e32 v24, 16, v7
	v_and_b32_e32 v7, 0xffff0000, v6
	v_lshlrev_b32_e32 v6, 16, v6
	v_add_f32_e32 v69, v142, v69
	v_pk_mul_f32 v[100:101], v[6:7], v[6:7]
	v_add_f32_e32 v69, v143, v69
	v_add_f32_e32 v69, v100, v69
	v_pk_mul_f32 v[76:77], v[24:25], v[24:25]
	v_add_f32_e32 v69, v101, v69
	v_and_b32_e32 v61, 0xffff0000, v60
	v_lshlrev_b32_e32 v60, 16, v60
	v_add_f32_e32 v69, v76, v69
	v_pk_mul_f32 v[174:175], v[60:61], v[60:61]
	v_add_f32_e32 v69, v77, v69
	v_add_f32_e32 v69, v174, v69
	v_pk_mul_f32 v[170:171], v[168:169], v[168:169]
	v_add_f32_e32 v69, v175, v69
	v_and_b32_e32 v157, 0xffff0000, v63
	v_lshlrev_b32_e32 v156, 16, v63
	v_and_b32_e32 v63, 0xffff0000, v62
	v_lshlrev_b32_e32 v62, 16, v62
	v_add_f32_e32 v69, v170, v69
	v_pk_mul_f32 v[162:163], v[62:63], v[62:63]
	v_add_f32_e32 v69, v171, v69
	v_add_f32_e32 v69, v162, v69
	v_pk_mul_f32 v[158:159], v[156:157], v[156:157]
	v_add_f32_e32 v69, v163, v69
	v_and_b32_e32 v153, 0xffff0000, v65
	v_lshlrev_b32_e32 v152, 16, v65
	v_and_b32_e32 v65, 0xffff0000, v64
	v_lshlrev_b32_e32 v64, 16, v64
	v_add_f32_e32 v69, v158, v69
	v_pk_mul_f32 v[148:149], v[64:65], v[64:65]
	v_add_f32_e32 v69, v159, v69
	v_add_f32_e32 v69, v148, v69
	v_pk_mul_f32 v[144:145], v[152:153], v[152:153]
	v_add_f32_e32 v69, v149, v69
	v_and_b32_e32 v27, 0xffff0000, v67
	v_lshlrev_b32_e32 v26, 16, v67
	v_and_b32_e32 v67, 0xffff0000, v66
	v_lshlrev_b32_e32 v66, 16, v66
	v_add_f32_e32 v69, v144, v69
	v_pk_mul_f32 v[102:103], v[66:67], v[66:67]
	v_add_f32_e32 v69, v145, v69
	v_add_f32_e32 v69, v102, v69
	v_pk_mul_f32 v[98:99], v[26:27], v[26:27]
	v_add_f32_e32 v69, v103, v69
	v_add_f32_e32 v69, v98, v69
	v_add_f32_e32 v69, v99, v69
	ds_bpermute_b32 v76, v196, v69
	v_cvt_pk_bf16_f32 v141, v70, v71
	v_pk_mul_f32 v[70:71], v[68:69], v[74:75] op_sel_hi:[0,1]
	v_pk_mul_f32 v[56:57], v[56:57], v[70:71]
	s_nop 0
	v_cvt_pk_bf16_f32 v142, v56, v57
	s_waitcnt lgkmcnt(0)
	v_add_f32_e32 v56, v69, v76
	v_fmamk_f32 v56, v56, 0x3c800000, v204
	v_rsq_f32_e32 v56, v56
	v_pk_mul_f32 v[68:69], v[68:69], v[72:73] op_sel_hi:[0,1]
	v_pk_mul_f32 v[58:59], v[58:59], v[68:69]
	v_pk_mul_f32 v[0:1], v[56:57], v[0:1] op_sel_hi:[0,1]
	s_waitcnt vmcnt(14)
	v_pk_mul_f32 v[0:1], v[32:33], v[0:1]
	v_pk_mul_f32 v[32:33], v[56:57], v[60:61] op_sel_hi:[0,1]
	s_waitcnt vmcnt(12)
	v_pk_mul_f32 v[32:33], v[40:41], v[32:33]
	v_pk_mul_f32 v[2:3], v[56:57], v[2:3] op_sel_hi:[0,1]
	s_waitcnt vmcnt(8)
	v_pk_mul_f32 v[40:41], v[78:79], v[32:33]
	v_pk_mul_f32 v[2:3], v[28:29], v[2:3]
	v_pk_fma_f32 v[40:41], v[48:49], v[0:1], v[40:41] neg_lo:[0,0,1] neg_hi:[0,0,1]
	v_pk_mul_f32 v[0:1], v[78:79], v[0:1]
	v_pk_mul_f32 v[28:29], v[56:57], v[62:63] op_sel_hi:[0,1]
	v_pk_fma_f32 v[0:1], v[48:49], v[32:33], v[0:1]
	v_pk_mul_f32 v[32:33], v[56:57], v[164:165] op_sel_hi:[0,1]
	v_pk_mul_f32 v[32:33], v[34:35], v[32:33]
	v_pk_mul_f32 v[34:35], v[56:57], v[168:169] op_sel_hi:[0,1]
	v_pk_mul_f32 v[34:35], v[42:43], v[34:35]
	v_pk_mul_f32 v[28:29], v[36:37], v[28:29]
	v_pk_mul_f32 v[42:43], v[80:81], v[34:35]
	v_pk_mul_f32 v[0:1], v[0:1], s[94:95] op_sel_hi:[1,0]
	v_pk_fma_f32 v[42:43], v[50:51], v[32:33], v[42:43] neg_lo:[0,0,1] neg_hi:[0,0,1]
	v_pk_mul_f32 v[32:33], v[80:81], v[32:33]
	v_cvt_pk_bf16_f32 v144, v0, v1
	v_pk_fma_f32 v[32:33], v[50:51], v[34:35], v[32:33]
	v_pk_mul_f32 v[34:35], v[52:53], v[28:29]
	v_pk_mul_f32 v[0:1], v[56:57], v[4:5] op_sel_hi:[0,1]
	v_pk_fma_f32 v[34:35], v[44:45], v[2:3], v[34:35] neg_lo:[0,0,1] neg_hi:[0,0,1]
	v_pk_mul_f32 v[2:3], v[52:53], v[2:3]
	s_waitcnt vmcnt(6)
	v_pk_mul_f32 v[0:1], v[82:83], v[0:1]
	v_pk_fma_f32 v[2:3], v[44:45], v[28:29], v[2:3]
	v_pk_mul_f32 v[28:29], v[56:57], v[150:151] op_sel_hi:[0,1]
	v_pk_mul_f32 v[2:3], v[2:3], s[94:95] op_sel_hi:[1,0]
	v_pk_mul_f32 v[28:29], v[30:31], v[28:29]
	v_pk_mul_f32 v[30:31], v[56:57], v[156:157] op_sel_hi:[0,1]
	v_cvt_pk_bf16_f32 v146, v2, v3
	v_pk_mul_f32 v[2:3], v[56:57], v[64:65] op_sel_hi:[0,1]
	v_pk_mul_f32 v[30:31], v[38:39], v[30:31]
	s_waitcnt vmcnt(4)
	v_pk_mul_f32 v[2:3], v[86:87], v[2:3]
	v_pk_mul_f32 v[36:37], v[54:55], v[30:31]
	s_waitcnt vmcnt(0)
; __device__ __forceinline__ unsigned cvt_pk_bf16(float lo, float hi) { f32x2 v = {lo, hi}; bf16x2_t b = __builtin_convertvector(v, bf16x2_t); return __builtin_bit_cast(unsigned, b); }
; __device__ __forceinline__ float bf2f(unsigned short v) { return __uint_as_float(((unsigned)v) << 16); }
; template <int DQK, bool MOBA>
; __device__ __forceinline__ void attn_unit(const Args& A, int b, int h, int qb, lptr lds) {
;     ...
; #pragma unroll
;                 for (int e = 0; e < 8; ++e) {
;                     const float x1 = bf2f((unsigned short)qf[(NS == 12 ? 8 : 0) + sp][e]) * scr * (e < 4 ? ga0[e & 3] : ga1[e & 3]);
;                     const float x2 = bf2f((unsigned short)qf[(NS == 12 ? 10 : 0) + sp][e]) * scr * (e < 4 ? gb0[e & 3] : gb1[e & 3]);
;                     const float c = e < 4 ? cc0[e & 3] : cc1[e & 3], sn = e < 4 ? ss0[e & 3] : ss1[e & 3];
;                     o1[e] = (x1 * c - x2 * sn) * A.qscale; o2[e] = (x2 * c + x1 * sn) * A.qscale;
;                 }
;                 u32x4 w1, w2;
;                 w1.x = cvt_pk_bf16(o1[0], o1[1]); w1.y = cvt_pk_bf16(o1[2], o1[3]); w1.z = cvt_pk_bf16(o1[4], o1[5]); w1.w = cvt_pk_bf16(o1[6], o1[7]);
;                 w2.x = cvt_pk_bf16(o2[0], o2[1]); w2.y = cvt_pk_bf16(o2[2], o2[3]); w2.z = cvt_pk_bf16(o2[4], o2[5]); w2.w = cvt_pk_bf16(o2[6], o2[7]);
;                 qf[(NS == 12 ? 8 : 0) + sp] = __builtin_bit_cast(bf16x8, w1); qf[(NS == 12 ? 10 : 0) + sp] = __builtin_bit_cast(bf16x8, w2);
;     ...
;         float qss = 0.f;
; #pragma unroll
;         for (int s = 0; s < NS; ++s)
; #pragma unroll
;             for (int e = 0; e < 8; ++e) { const float f = bf2f((unsigned short)qf[s][e]); qss += f * f; }
;         qss += __shfl_xor(qss, 32);
;         float gmx = fmaxf(fabsf(A.gk_n[lane]), fabsf(A.gk_n[lane + 64]));
	v_pk_mul_f32 v[4:5], v[94:95], v[2:3]
	v_pk_fma_f32 v[36:37], v[46:47], v[28:29], v[36:37] neg_lo:[0,0,1] neg_hi:[0,0,1]
	v_pk_mul_f32 v[28:29], v[54:55], v[28:29]
	v_pk_fma_f32 v[4:5], v[90:91], v[0:1], v[4:5] neg_lo:[0,0,1] neg_hi:[0,0,1]
	v_pk_mul_f32 v[0:1], v[94:95], v[0:1]
	v_pk_fma_f32 v[28:29], v[46:47], v[30:31], v[28:29]
	v_pk_fma_f32 v[0:1], v[90:91], v[2:3], v[0:1]
	v_pk_mul_f32 v[28:29], v[28:29], s[94:95] op_sel_hi:[1,0]
	v_pk_mul_f32 v[0:1], v[0:1], s[94:95] op_sel_hi:[1,0]
	v_cvt_pk_bf16_f32 v147, v28, v29
	v_pk_mul_f32 v[28:29], v[56:57], v[152:153] op_sel_hi:[0,1]
	v_cvt_pk_bf16_f32 v152, v0, v1
	v_and_b32_e32 v0, 0xffff0000, v112
	v_lshlrev_b32_e32 v1, 16, v112
	v_mul_f32_e32 v0, v0, v0
	v_fmac_f32_e32 v0, v1, v1
	v_lshlrev_b32_e32 v1, 16, v113
	v_fmac_f32_e32 v0, v1, v1
	v_and_b32_e32 v1, 0xffff0000, v113
	v_fmac_f32_e32 v0, v1, v1
	v_lshlrev_b32_e32 v1, 16, v114
	v_fmac_f32_e32 v0, v1, v1
	v_and_b32_e32 v1, 0xffff0000, v114
	v_fmac_f32_e32 v0, v1, v1
	v_lshlrev_b32_e32 v1, 16, v115
	v_fmac_f32_e32 v0, v1, v1
	v_and_b32_e32 v1, 0xffff0000, v115
	v_fmac_f32_e32 v0, v1, v1
	v_lshlrev_b32_e32 v1, 16, v116
	v_fmac_f32_e32 v0, v1, v1
	v_and_b32_e32 v1, 0xffff0000, v116
	v_fmac_f32_e32 v0, v1, v1
	v_lshlrev_b32_e32 v1, 16, v117
	v_fmac_f32_e32 v0, v1, v1
	v_and_b32_e32 v1, 0xffff0000, v117
	v_fmac_f32_e32 v0, v1, v1
	v_lshlrev_b32_e32 v1, 16, v118
	v_fmac_f32_e32 v0, v1, v1
	v_and_b32_e32 v1, 0xffff0000, v118
	v_fmac_f32_e32 v0, v1, v1
	v_lshlrev_b32_e32 v1, 16, v119
	v_fmac_f32_e32 v0, v1, v1
	v_and_b32_e32 v1, 0xffff0000, v119
	v_fmac_f32_e32 v0, v1, v1
	v_lshlrev_b32_e32 v1, 16, v120
	v_fmac_f32_e32 v0, v1, v1
	v_and_b32_e32 v1, 0xffff0000, v120
	v_fmac_f32_e32 v0, v1, v1
	v_lshlrev_b32_e32 v1, 16, v121
	v_fmac_f32_e32 v0, v1, v1
	v_and_b32_e32 v1, 0xffff0000, v121
	v_fmac_f32_e32 v0, v1, v1
	v_lshlrev_b32_e32 v1, 16, v122
	v_fmac_f32_e32 v0, v1, v1
	v_and_b32_e32 v1, 0xffff0000, v122
	v_fmac_f32_e32 v0, v1, v1
	v_lshlrev_b32_e32 v1, 16, v123
	v_fmac_f32_e32 v0, v1, v1
	v_and_b32_e32 v1, 0xffff0000, v123
	v_fmac_f32_e32 v0, v1, v1
	v_lshlrev_b32_e32 v1, 16, v124
	v_fmac_f32_e32 v0, v1, v1
	v_and_b32_e32 v1, 0xffff0000, v124
	v_fmac_f32_e32 v0, v1, v1
	v_lshlrev_b32_e32 v1, 16, v125
	v_fmac_f32_e32 v0, v1, v1
	v_and_b32_e32 v1, 0xffff0000, v125
	v_fmac_f32_e32 v0, v1, v1
	v_lshlrev_b32_e32 v1, 16, v126
	v_fmac_f32_e32 v0, v1, v1
	v_and_b32_e32 v1, 0xffff0000, v126
	v_fmac_f32_e32 v0, v1, v1
	v_lshlrev_b32_e32 v1, 16, v127
	v_fmac_f32_e32 v0, v1, v1
	v_and_b32_e32 v1, 0xffff0000, v127
	v_fmac_f32_e32 v0, v1, v1
	v_lshlrev_b32_e32 v1, 16, v128
	v_fmac_f32_e32 v0, v1, v1
	v_and_b32_e32 v1, 0xffff0000, v128
	v_fmac_f32_e32 v0, v1, v1
	v_lshlrev_b32_e32 v1, 16, v129
	v_fmac_f32_e32 v0, v1, v1
	v_and_b32_e32 v1, 0xffff0000, v129
	v_fmac_f32_e32 v0, v1, v1
	v_lshlrev_b32_e32 v1, 16, v130
	v_fmac_f32_e32 v0, v1, v1
	v_and_b32_e32 v1, 0xffff0000, v130
	v_fmac_f32_e32 v0, v1, v1
	v_lshlrev_b32_e32 v1, 16, v131
	v_fmac_f32_e32 v0, v1, v1
	v_and_b32_e32 v1, 0xffff0000, v131
	v_fmac_f32_e32 v0, v1, v1
	v_lshlrev_b32_e32 v1, 16, v132
	v_fmac_f32_e32 v0, v1, v1
	v_and_b32_e32 v1, 0xffff0000, v132
	v_fmac_f32_e32 v0, v1, v1
	v_lshlrev_b32_e32 v1, 16, v133
	v_fmac_f32_e32 v0, v1, v1
	v_and_b32_e32 v1, 0xffff0000, v133
	v_fmac_f32_e32 v0, v1, v1
	v_lshlrev_b32_e32 v1, 16, v134
	v_fmac_f32_e32 v0, v1, v1
	v_and_b32_e32 v1, 0xffff0000, v134
	v_fmac_f32_e32 v0, v1, v1
	v_lshlrev_b32_e32 v1, 16, v135
	v_fmac_f32_e32 v0, v1, v1
	v_and_b32_e32 v1, 0xffff0000, v135
	v_fmac_f32_e32 v0, v1, v1
	v_lshlrev_b32_e32 v1, 16, v136
	v_fmac_f32_e32 v0, v1, v1
	v_and_b32_e32 v1, 0xffff0000, v136
	v_fmac_f32_e32 v0, v1, v1
	v_lshlrev_b32_e32 v1, 16, v137
	v_fmac_f32_e32 v0, v1, v1
	v_and_b32_e32 v1, 0xffff0000, v137
	v_pk_mul_f32 v[6:7], v[56:57], v[6:7] op_sel_hi:[0,1]
	v_fmac_f32_e32 v0, v1, v1
	v_lshlrev_b32_e32 v1, 16, v138
	v_pk_mul_f32 v[4:5], v[4:5], s[94:95] op_sel_hi:[1,0]
	v_pk_mul_f32 v[6:7], v[20:21], v[6:7]
	v_pk_mul_f32 v[20:21], v[56:57], v[66:67] op_sel_hi:[0,1]
	v_fmac_f32_e32 v0, v1, v1
	v_lshlrev_b32_e32 v1, 2, v110
	v_pk_mul_f32 v[16:17], v[16:17], v[20:21]
	v_cvt_pk_bf16_f32 v156, v4, v5
	global_load_dword v4, v1, s[38:39]
	global_load_dword v5, v1, s[38:39] offset:256
	v_pk_mul_f32 v[20:21], v[12:13], v[16:17]
	v_pk_mul_f32 v[2:3], v[56:57], v[104:105] op_sel_hi:[0,1]
	v_pk_fma_f32 v[20:21], v[8:9], v[6:7], v[20:21] neg_lo:[0,0,1] neg_hi:[0,0,1]
	v_pk_mul_f32 v[6:7], v[12:13], v[6:7]
	v_pk_mul_f32 v[28:29], v[88:89], v[28:29]
	v_pk_fma_f32 v[6:7], v[8:9], v[16:17], v[6:7]
	v_pk_mul_f32 v[2:3], v[84:85], v[2:3]
	v_pk_mul_f32 v[6:7], v[6:7], s[94:95] op_sel_hi:[1,0]
	v_pk_mul_f32 v[30:31], v[96:97], v[28:29]
	v_cvt_pk_bf16_f32 v154, v6, v7
	global_load_dword v6, v1, s[40:41]
	v_pk_fma_f32 v[30:31], v[92:93], v[2:3], v[30:31] neg_lo:[0,0,1] neg_hi:[0,0,1]
	v_pk_mul_f32 v[2:3], v[96:97], v[2:3]
	v_and_b32_e32 v1, 0xffff0000, v140
	v_pk_fma_f32 v[2:3], v[92:93], v[28:29], v[2:3]
	v_cvt_pk_bf16_f32 v143, v58, v59
	v_pk_mul_f32 v[2:3], v[2:3], s[94:95] op_sel_hi:[1,0]
	v_pk_mul_f32 v[40:41], v[40:41], s[94:95] op_sel_hi:[1,0]
	v_cvt_pk_bf16_f32 v153, v2, v3
	v_and_b32_e32 v2, 0xffff0000, v138
	v_fmac_f32_e32 v0, v2, v2
	v_lshlrev_b32_e32 v2, 16, v139
	v_fmac_f32_e32 v0, v2, v2
	v_and_b32_e32 v2, 0xffff0000, v139
	v_fmac_f32_e32 v0, v2, v2
	v_lshlrev_b32_e32 v2, 16, v140
	v_fmac_f32_e32 v0, v2, v2
	v_fmac_f32_e32 v0, v1, v1
	v_lshlrev_b32_e32 v1, 16, v141
	v_fmac_f32_e32 v0, v1, v1
	v_and_b32_e32 v1, 0xffff0000, v141
	v_fmac_f32_e32 v0, v1, v1
	v_lshlrev_b32_e32 v1, 16, v142
	v_fmac_f32_e32 v0, v1, v1
	v_and_b32_e32 v1, 0xffff0000, v142
; __device__ __forceinline__ float bf2f(unsigned short v) { return __uint_as_float(((unsigned)v) << 16); }
; template <int DQK, bool MOBA>
; __device__ __forceinline__ void attn_unit(const Args& A, int b, int h, int qb, lptr lds) {
;     ...
;         float qss = 0.f;
; #pragma unroll
;         for (int s = 0; s < NS; ++s)
; #pragma unroll
;             for (int e = 0; e < 8; ++e) { const float f = bf2f((unsigned short)qf[s][e]); qss += f * f; }
;         qss += __shfl_xor(qss, 32);
;         float gmx = fmaxf(fabsf(A.gk_n[lane]), fabsf(A.gk_n[lane + 64]));
;         float grx = (DQK == 192) ? fabsf(A.gk_r[lane]) : 0.f;
;         float bmx = (MOBA && lane < 32) ? fabsf(A.relb[lane * 8 + h]) * 1.4426950408889634f : 0.f;
; #pragma unroll
;         for (int o_ = 1; o_ < 64; o_ <<= 1) { gmx = fmaxf(gmx, __shfl_xor(gmx, o_)); grx = fmaxf(grx, __shfl_xor(grx, o_)); bmx = fmaxf(bmx, __shfl_xor(bmx, o_)); }
;         negm = -(sqrtf(qss * (128.0f * gmx * gmx + 64.0f * grx * grx)) * 1.01f + bmx + 0.01f);
	v_fmac_f32_e32 v0, v1, v1
	v_lshlrev_b32_e32 v1, 16, v143
	v_cvt_pk_bf16_f32 v148, v40, v41
	v_fmac_f32_e32 v0, v1, v1
	v_and_b32_e32 v1, 0xffff0000, v143
	v_pk_mul_f32 v[42:43], v[42:43], s[94:95] op_sel_hi:[1,0]
	v_fmac_f32_e32 v0, v1, v1
	v_lshlrev_b32_e32 v1, 16, v148
	v_cvt_pk_bf16_f32 v149, v42, v43
	v_fmac_f32_e32 v0, v1, v1
	v_and_b32_e32 v1, 0xffff0000, v148
	v_pk_mul_f32 v[34:35], v[34:35], s[94:95] op_sel_hi:[1,0]
	v_fmac_f32_e32 v0, v1, v1
	v_lshlrev_b32_e32 v1, 16, v149
	v_cvt_pk_bf16_f32 v150, v34, v35
	v_fmac_f32_e32 v0, v1, v1
	v_and_b32_e32 v1, 0xffff0000, v149
	v_pk_mul_f32 v[36:37], v[36:37], s[94:95] op_sel_hi:[1,0]
	v_fmac_f32_e32 v0, v1, v1
	v_lshlrev_b32_e32 v1, 16, v150
	v_cvt_pk_bf16_f32 v151, v36, v37
	v_fmac_f32_e32 v0, v1, v1
	v_and_b32_e32 v1, 0xffff0000, v150
	v_fmac_f32_e32 v0, v1, v1
	v_lshlrev_b32_e32 v1, 16, v151
	v_fmac_f32_e32 v0, v1, v1
	v_and_b32_e32 v1, 0xffff0000, v151
	v_pk_mul_f32 v[30:31], v[30:31], s[94:95] op_sel_hi:[1,0]
	v_pk_mul_f32 v[12:13], v[56:57], v[26:27] op_sel_hi:[0,1]
	v_fmac_f32_e32 v0, v1, v1
	v_lshlrev_b32_e32 v1, 16, v156
	v_pk_mul_f32 v[8:9], v[56:57], v[24:25] op_sel_hi:[0,1]
	v_pk_mul_f32 v[12:13], v[18:19], v[12:13]
	v_cvt_pk_bf16_f32 v157, v30, v31
	v_fmac_f32_e32 v0, v1, v1
	v_and_b32_e32 v1, 0xffff0000, v156
	v_pk_mul_f32 v[20:21], v[20:21], s[94:95] op_sel_hi:[1,0]
	v_pk_mul_f32 v[8:9], v[22:23], v[8:9]
	v_pk_mul_f32 v[16:17], v[14:15], v[12:13]
	v_fmac_f32_e32 v0, v1, v1
	v_lshlrev_b32_e32 v1, 16, v157
	v_pk_fma_f32 v[16:17], v[10:11], v[8:9], v[16:17] neg_lo:[0,0,1] neg_hi:[0,0,1]
	v_cvt_pk_bf16_f32 v158, v20, v21
	v_fmac_f32_e32 v0, v1, v1
	v_and_b32_e32 v1, 0xffff0000, v157
	v_pk_mul_f32 v[16:17], v[16:17], s[94:95] op_sel_hi:[1,0]
	v_fmac_f32_e32 v0, v1, v1
	v_lshlrev_b32_e32 v1, 16, v158
	v_cvt_pk_bf16_f32 v159, v16, v17
	v_fmac_f32_e32 v0, v1, v1
	v_and_b32_e32 v1, 0xffff0000, v158
	v_fmac_f32_e32 v0, v1, v1
	v_lshlrev_b32_e32 v1, 16, v159
	v_pk_mul_f32 v[32:33], v[32:33], s[94:95] op_sel_hi:[1,0]
	v_fmac_f32_e32 v0, v1, v1
	v_and_b32_e32 v1, 0xffff0000, v159
	v_cvt_pk_bf16_f32 v145, v32, v33
	v_fmac_f32_e32 v0, v1, v1
	v_lshlrev_b32_e32 v1, 16, v144
	v_fmac_f32_e32 v0, v1, v1
	v_and_b32_e32 v1, 0xffff0000, v144
	v_and_b32_e32 v3, 0xffff0000, v145
	v_lshlrev_b32_e32 v2, 16, v145
	v_fmac_f32_e32 v0, v1, v1
	v_pk_mul_f32 v[2:3], v[2:3], v[2:3]
	v_and_b32_e32 v1, 0xffff0000, v146
	v_add_f32_e32 v0, v2, v0
	v_add_f32_e32 v2, v3, v0
	v_lshlrev_b32_e32 v0, 16, v146
	v_pk_mul_f32 v[0:1], v[0:1], v[0:1]
	v_pk_mul_f32 v[8:9], v[14:15], v[8:9]
	v_add_f32_e32 v0, v0, v2
	v_add_f32_e32 v2, v1, v0
	v_lshlrev_b32_e32 v1, 16, v147
	v_and_b32_e32 v0, 0xffff0000, v147
	v_pk_mul_f32 v[0:1], v[0:1], v[0:1]
	v_pk_fma_f32 v[8:9], v[10:11], v[12:13], v[8:9]
	v_add_f32_e32 v1, v1, v2
	v_add_f32_e32 v2, v0, v1
	v_and_b32_e32 v1, 0xffff0000, v152
	v_lshlrev_b32_e32 v0, 16, v152
	v_pk_mul_f32 v[0:1], v[0:1], v[0:1]
	v_pk_mul_f32 v[8:9], v[8:9], s[94:95] op_sel_hi:[1,0]
	v_add_f32_e32 v0, v0, v2
	v_add_f32_e32 v2, v1, v0
	s_waitcnt vmcnt(1)
	v_max_f32_e64 v0, |v5|, |v5|
	v_max_f32_e64 v1, |v4|, |v4|
	v_max_f32_e32 v3, v1, v0
	v_xor_b32_e32 v0, 1, v206
	v_cmp_lt_i32_e32 vcc, v0, v109
	s_waitcnt vmcnt(0)
	v_and_b32_e32 v1, 0x7fffffff, v6
	v_cvt_pk_bf16_f32 v155, v8, v9
	v_cndmask_b32_e32 v0, v206, v0, vcc
	v_lshlrev_b32_e32 v0, 2, v0
	ds_bpermute_b32 v4, v0, v3
	ds_bpermute_b32 v5, v0, v1
	v_and_b32_e32 v1, 0xffff0000, v153
	v_lshlrev_b32_e32 v0, 16, v153
	v_pk_mul_f32 v[0:1], v[0:1], v[0:1]
	s_waitcnt lgkmcnt(1)
	v_max_f32_e32 v4, v4, v4
	v_max_f32_e32 v3, v3, v4
	s_waitcnt lgkmcnt(0)
	v_max_f32_e32 v4, v5, v5
	v_max_f32_e64 v5, |v6|, |v6|
	v_xor_b32_e32 v6, 2, v206
	v_cmp_lt_i32_e32 vcc, v6, v109
	v_max_f32_e32 v4, v5, v4
	v_add_f32_e32 v0, v0, v2
	v_cndmask_b32_e32 v6, v206, v6, vcc
	v_lshlrev_b32_e32 v6, 2, v6
	ds_bpermute_b32 v7, v6, v3
	ds_bpermute_b32 v5, v6, v4
	v_and_b32_e32 v32, 15, v106
	v_lshlrev_b32_e32 v186, 4, v32
	v_add_u32_e32 v14, s4, v199
	s_waitcnt lgkmcnt(1)
	v_max_f32_e32 v2, v7, v7
	v_max_f32_e32 v2, v3, v2
	s_waitcnt lgkmcnt(0)
	v_max_f32_e32 v3, v5, v5
	v_xor_b32_e32 v5, 4, v206
	v_cmp_lt_i32_e32 vcc, v5, v109
	v_max_f32_e32 v3, v4, v3
	v_ashrrev_i32_e32 v15, 31, v14
	v_cndmask_b32_e32 v5, v206, v5, vcc
	v_lshlrev_b32_e32 v5, 2, v5
	ds_bpermute_b32 v6, v5, v2
	ds_bpermute_b32 v4, v5, v3
	v_add_f32_e32 v5, v1, v0
	v_and_b32_e32 v1, 0xffff0000, v154
	v_lshlrev_b64 v[14:15], 7, v[14:15]
	s_waitcnt lgkmcnt(1)
	v_max_f32_e32 v0, v6, v6
	v_max_f32_e32 v2, v2, v0
	s_waitcnt lgkmcnt(0)
	v_max_f32_e32 v0, v4, v4
	v_xor_b32_e32 v4, 8, v206
	v_cmp_lt_i32_e32 vcc, v4, v109
	v_max_f32_e32 v3, v3, v0
	v_lshlrev_b32_e32 v0, 16, v154
	v_cndmask_b32_e32 v4, v206, v4, vcc
	v_lshlrev_b32_e32 v4, 2, v4
	ds_bpermute_b32 v6, v4, v2
	ds_bpermute_b32 v4, v4, v3
	v_pk_mul_f32 v[0:1], v[0:1], v[0:1]
	v_lshlrev_b32_e32 v16, 4, v106
	v_add_f32_e32 v0, v0, v5
	s_waitcnt lgkmcnt(1)
	v_max_f32_e32 v6, v6, v6
	v_max_f32_e32 v2, v2, v6
	v_xor_b32_e32 v6, 16, v206
	v_cmp_lt_i32_e32 vcc, v6, v109
	s_waitcnt lgkmcnt(0)
	v_max_f32_e32 v4, v4, v4
	v_max_f32_e32 v3, v3, v4
	v_cndmask_b32_e32 v6, v206, v6, vcc
	v_lshlrev_b32_e32 v6, 2, v6
	ds_bpermute_b32 v7, v6, v2
	ds_bpermute_b32 v4, v6, v3
	v_add_f32_e32 v1, v1, v0
	v_and_b32_e32 v5, 0xffff0000, v155
	v_lshl_add_u64 v[14:15], s[86:87], 0, v[14:15]
	s_waitcnt lgkmcnt(1)
	v_max_f32_e32 v0, v7, v7
	v_max_f32_e32 v0, v2, v0
	s_waitcnt lgkmcnt(0)
	v_max_f32_e32 v2, v4, v4
	ds_bpermute_b32 v4, v196, v0
	v_max_f32_e32 v6, v3, v2
	ds_bpermute_b32 v7, v196, v6
	v_lshlrev_b32_e32 v3, 16, v155
	v_mov_b32_e32 v183, v3
	s_waitcnt lgkmcnt(1)
; template <int DQK, bool MOBA>
; __device__ __forceinline__ void attn_unit(const Args& A, int b, int h, int qb, lptr lds) {
;     ...
;         negm = -(sqrtf(qss * (128.0f * gmx * gmx + 64.0f * grx * grx)) * 1.01f + bmx + 0.01f);
;     }
;     const int NT = 4 * (own + 1);
;     u32x4 kr0, kr1, kr2, vr0, vr1; int pkr = 0;
;     kr2 = (u32x4){0u, 0u, 0u, 0u};
;     ...
;     f32x16 o[4];
; #pragma unroll
;     for (int d = 0; d < 4; ++d)
; #pragma unroll
;         for (int r = 0; r < 16; ++r) o[d][r] = 0.f;
;     float lrow = 0.f;
;     ATT_LOAD(0); ATT_WRITE(0);
;     if (NT > 1) ATT_LOAD(1);
;     __syncthreads();
	v_max_f32_e32 v2, v4, v4
	v_max_f32_e32 v2, v0, v2
	s_waitcnt lgkmcnt(0)
	v_max_f32_e32 v0, v7, v7
	v_max_f32_e32 v4, v6, v0
	v_pk_mul_f32 v[8:9], v[2:3], v[182:183]
	v_mov_b32_e32 v0, v2
	v_pk_mul_f32 v[8:9], v[2:3], v[8:9]
	v_pk_fma_f32 v[0:1], v[2:3], v[182:183], v[0:1]
	v_mul_f32_e32 v6, 0x42800000, v4
	v_mov_b32_e32 v9, v1
	v_mov_b32_e32 v7, v5
	v_pk_fma_f32 v[26:27], v[4:5], v[6:7], v[8:9]
	ds_bpermute_b32 v30, v196, v27
	v_ashrrev_i32_e32 v0, 4, v106
	v_ashrrev_i32_e32 v1, 31, v0
	v_lshlrev_b64 v[2:3], 11, v[0:1]
	v_lshl_add_u64 v[4:5], s[0:1], 0, v[2:3]
	s_waitcnt lgkmcnt(0)
	v_add_f32_e32 v27, v27, v30
	v_mul_f32_e32 v26, v26, v27
	v_mul_f32_e32 v27, 0x4f800000, v26
	v_cmp_gt_f32_e32 vcc, s35, v26
	v_lshl_add_u64 v[6:7], v[4:5], 0, v[186:187]
	v_add_u32_e32 v4, 32, v0
	v_cndmask_b32_e32 v26, v26, v27, vcc
	v_ashrrev_i32_e32 v5, 31, v4
	v_sqrt_f32_e32 v27, v26
	v_lshlrev_b64 v[28:29], 11, v[4:5]
	v_lshl_add_u64 v[8:9], s[0:1], 0, v[28:29]
	s_add_u32 s0, s92, s44
	s_addc_u32 s1, s93, s45
	s_add_u32 s0, s0, s6
	v_add_u32_e32 v30, -1, v27
	s_addc_u32 s1, s1, s7
	v_fma_f32 v31, -v30, v27, v26
	v_lshl_add_u64 v[18:19], s[0:1], 0, v[2:3]
	v_lshl_add_u64 v[22:23], s[0:1], 0, v[28:29]
	v_cmp_ge_f32_e64 s[0:1], 0, v31
	v_add_u32_e32 v31, 1, v27
	v_and_b32_e32 v188, 0x70, v16
	v_cndmask_b32_e64 v30, v27, v30, s[0:1]
	v_fma_f32 v27, -v31, v27, v26
	v_cmp_lt_f32_e64 s[0:1], 0, v27
	v_lshl_add_u64 v[10:11], v[8:9], 0, v[186:187]
	v_lshl_add_u64 v[14:15], v[14:15], 0, v[188:189]
	v_cndmask_b32_e64 v27, v30, v31, s[0:1]
	v_mul_f32_e32 v30, 0x37800000, v27
	v_cndmask_b32_e32 v27, v27, v30, vcc
	v_cmp_class_f32_e32 vcc, v26, v205
	s_mov_b32 s0, 0x3f8147ae
	s_nop 0
	s_nop 0
	s_nop 0
	v_cndmask_b32_e32 v26, v27, v26, vcc
	v_fma_f32 v26, v26, s0, 0
	v_add_f32_e32 v33, 0x3c23d70a, v26
	v_mov_b32_e32 v26, s15
	s_movk_i32 s0, 0xffe0
	v_bfi_b32 v197, s0, v26, v106
	s_or_b32 s0, s4, 64
	s_ashr_i32 s1, s0, 31
	s_lshl_b64 s[44:45], s[0:1], 11
	s_add_u32 s1, s92, s44
	s_addc_u32 s4, s93, s45
	s_add_u32 s46, s1, s6
	s_nop 0
	v_lshl_add_u64 v[22:23], v[22:23], 0, v[186:187]
	s_addc_u32 s47, s4, s7
	s_nop 0
	v_lshl_add_u64 v[26:27], s[46:47], 0, v[28:29]
	v_add_u32_e32 v30, s0, v199
	s_add_u32 s0, s90, s44
	v_lshl_add_u64 v[18:19], v[18:19], 0, v[186:187]
	v_lshl_add_u64 v[26:27], v[26:27], 0, v[186:187]
	v_ashrrev_i32_e32 v31, 31, v30
	s_addc_u32 s1, s91, s45
	s_nop 0
	v_lshlrev_b64 v[30:31], 7, v[30:31]
	global_load_dwordx4 v[160:163], v[26:27], off
	v_lshl_add_u64 v[26:27], s[46:47], 0, v[2:3]
	s_add_u32 s0, s0, s6
	v_lshl_add_u64 v[26:27], v[26:27], 0, v[186:187]
	v_lshl_add_u64 v[30:31], s[86:87], 0, v[30:31]
	s_addc_u32 s1, s1, s7
	v_lshl_add_u64 v[30:31], v[30:31], 0, v[188:189]
	global_load_dwordx4 v[164:167], v[26:27], off
	global_load_dwordx4 v[172:175], v[30:31], off
	v_lshl_add_u64 v[26:27], s[0:1], 0, v[28:29]
	v_lshl_add_u64 v[26:27], v[26:27], 0, v[186:187]
	v_lshl_add_u64 v[2:3], s[0:1], 0, v[2:3]
	v_lshl_add_u64 v[2:3], v[2:3], 0, v[186:187]
	global_load_dwordx4 v[168:171], v[26:27], off
	global_load_dwordx4 v[176:179], v[2:3], off
	s_movk_i32 s0, 0x190
	v_mul_lo_u32 v200, v0, s0
	v_mul_lo_u32 v210, v199, s0
	s_movk_i32 s0, 0xffb0
	v_lshlrev_b64 v[26:27], 10, v[0:1]
	v_add3_u32 v1, 0, v200, v186
	v_add3_u32 v2, 0, v210, v188
	v_mul_lo_u32 v211, v0, s12
	v_mul_lo_u32 v0, v0, s0
	s_movk_i32 s0, 0x3200
	v_lshlrev_b32_e32 v183, 2, v107
	s_add_u32 s4, s90, s6
	v_lshlrev_b32_e32 v28, 3, v32
	v_lshlrev_b64 v[30:31], 10, v[4:5]
	s_addc_u32 s15, s91, s7
	v_xor_b32_e32 v64, 0x80000000, v33
	s_add_u32 s6, s92, s6
	v_mov_b32_e32 v3, v181
	v_mov_b32_e32 v4, v181
	v_mov_b32_e32 v5, v181
	v_lshlrev_b64 v[192:193], 1, v[26:27]
	v_lshlrev_b64 v[194:195], 1, v[30:31]
	v_add_u32_e32 v201, 0x3200, v200
	v_add_u32_e32 v212, 0x2800, v211
	v_mov_b32_e32 v65, v64
	v_mov_b32_e32 v66, v64
	v_mov_b32_e32 v67, v64
	v_mov_b32_e32 v68, v64
	v_mov_b32_e32 v69, v64
	v_mov_b32_e32 v70, v64
	v_mov_b32_e32 v71, v64
	v_mov_b32_e32 v72, v64
	v_mov_b32_e32 v73, v64
	v_mov_b32_e32 v74, v64
	v_mov_b32_e32 v75, v64
	v_mov_b32_e32 v76, v64
	v_mov_b32_e32 v77, v64
	v_mov_b32_e32 v78, v64
	v_mov_b32_e32 v79, v64
	v_lshl_add_u64 v[190:191], s[86:87], 0, v[188:189]
	s_waitcnt vmcnt(9)
	ds_write_b128 v1, v[214:217]
	s_waitcnt vmcnt(8)
	ds_write_b128 v1, v[218:221] offset:12800
	v_mov_b32_e32 v6, v181
	v_mov_b32_e32 v7, v181
	v_mov_b32_e32 v8, v181
	v_mov_b32_e32 v9, v181
	v_mov_b32_e32 v10, v181
	v_mov_b32_e32 v11, v181
	v_mov_b32_e32 v12, v181
	v_mov_b32_e32 v13, v181
	s_addc_u32 s7, s93, s7
	s_or_b32 s13, s13, 0xc0
	v_mov_b32_e32 v187, 0
	s_waitcnt vmcnt(7)
	ds_write_b128 v2, v[222:225] offset:256
	v_add_u32_e32 v2, v1, v0
	v_add3_u32 v0, v1, s0, v0
	s_waitcnt vmcnt(6)
	ds_write_b128 v0, v[226:229] offset:48640
	v_mul_u32_u24_e32 v0, 0x190, v108
	v_add3_u32 v213, 0, v0, v180
	v_lshrrev_b32_e32 v0, 2, v106
	v_and_or_b32 v0, v0, 3, v183
	v_lshlrev_b32_e32 v1, 1, v106
	v_mad_u32_u24 v0, v0, s12, 0
	v_and_b32_e32 v1, 32, v1
	s_waitcnt vmcnt(5)
	ds_write_b128 v2, v[230:233] offset:51200
	v_lshlrev_b32_e32 v2, 3, v106
	v_and_b32_e32 v2, 24, v2
	v_mov_b32_e32 v14, v181
	v_mov_b32_e32 v15, v181
	v_add3_u32 v198, v0, v1, v2
	v_mov_b32_e32 v0, v181
	v_mov_b32_e32 v1, v181
	v_mov_b32_e32 v2, v181
	v_lshlrev_b32_e32 v180, 1, v28
	v_mov_b64_e32 v[30:31], v[14:15]
	v_mov_b64_e32 v[46:47], v[14:15]
	v_mov_b64_e32 v[62:63], v[14:15]
	v_mov_b64_e32 v[28:29], v[12:13]
	v_mov_b64_e32 v[26:27], v[10:11]
	v_mov_b64_e32 v[24:25], v[8:9]
	v_mov_b64_e32 v[22:23], v[6:7]
	v_mov_b64_e32 v[20:21], v[4:5]
	v_mov_b64_e32 v[18:19], v[2:3]
	v_mov_b64_e32 v[16:17], v[0:1]
	v_mov_b64_e32 v[44:45], v[12:13]
	v_mov_b64_e32 v[42:43], v[10:11]
	v_mov_b64_e32 v[40:41], v[8:9]
	v_mov_b64_e32 v[38:39], v[6:7]
	v_mov_b64_e32 v[36:37], v[4:5]
	v_mov_b64_e32 v[34:35], v[2:3]
	v_mov_b64_e32 v[32:33], v[0:1]
	v_mov_b64_e32 v[60:61], v[12:13]
	v_mov_b64_e32 v[58:59], v[10:11]
	v_mov_b64_e32 v[56:57], v[8:9]
	v_mov_b64_e32 v[54:55], v[6:7]
	v_mov_b64_e32 v[52:53], v[4:5]
	v_mov_b64_e32 v[50:51], v[2:3]
	v_mov_b64_e32 v[48:49], v[0:1]
	s_waitcnt lgkmcnt(0)
	s_barrier
	s_branch .LBB0_812
